# nt hint on the prologue's read-once x loads (f32 input stream), on top of v40
# speedup vs baseline: 1.0410x; 1.0134x over previous
; __device__ __forceinline__ void prologue(const Params& p, LAS unsigned char* lds) {
;     ...
;         for (int m0 = gw; m0 < MREAL; m0 += 4 * NGW) {
;             f32x4 v[4][4];
; #pragma unroll
;             for (int r = 0; r < 4; ++r) { const int m = m0 + r * NGW;
;                 if (m < MREAL) { const f32x4* xr = (const f32x4*)(m < MP ? p.xp + (size_t)m * DM : p.xs + (size_t)(m - MP) * DM) + lane;
; #pragma unroll
;                     for (int j = 0; j < 4; ++j) v[r][j] = xr[64 * j]; } }
.LBB0_69:
	s_add_i32 s8, s0, 0xffff8000
	s_ashr_i32 s1, s0, 31
	s_cmp_lt_i32 s0, 0x8000
	v_readlane_b32 s52, v249, 4
	s_cselect_b32 s9, s1, 0
	s_cselect_b32 s8, s0, s8
	v_readlane_b32 s53, v249, 5
	v_readlane_b32 s54, v249, 6
	v_readlane_b32 s55, v249, 7
	s_cselect_b32 s10, s53, s55
	s_cselect_b32 s11, s52, s54
	s_lshl_b64 s[8:9], s[8:9], 12
	s_add_u32 s8, s11, s8
	s_addc_u32 s9, s10, s9
	global_load_dwordx4 v[60:63], v64, s[8:9] nt
	global_load_dwordx4 v[56:59], v64, s[8:9] offset:1024 nt
	s_waitcnt lgkmcnt(0)
	global_load_dwordx4 v[52:55], v64, s[8:9] offset:2048 nt
	global_load_dwordx4 v[48:51], v64, s[8:9] offset:3072 nt
	s_add_i32 s8, s0, s6
	s_cmp_lt_i32 s8, 0x8080
	s_cselect_b64 s[18:19], -1, 0
	s_cmp_gt_i32 s8, 0x807f
	v_readlane_b32 s56, v249, 8
	v_readlane_b32 s57, v249, 9
	v_readlane_b32 s58, v249, 10
	v_readlane_b32 s59, v249, 11
	v_readlane_b32 s60, v249, 12
	v_readlane_b32 s61, v249, 13
	v_readlane_b32 s62, v249, 14
	v_readlane_b32 s63, v249, 15
	v_readlane_b32 s64, v249, 16
	v_readlane_b32 s65, v249, 17
	v_readlane_b32 s66, v249, 18
	v_readlane_b32 s67, v249, 19
	s_cbranch_scc1 .LBB0_71
	s_ashr_i32 s9, s8, 31
	s_add_i32 s10, s8, 0xffff8000
	s_cmp_lt_i32 s8, 0x8000
	v_readlane_b32 s52, v249, 4
	s_cselect_b32 s11, s9, 0
	s_cselect_b32 s10, s8, s10
	v_readlane_b32 s53, v249, 5
	v_readlane_b32 s54, v249, 6
	v_readlane_b32 s55, v249, 7
	s_cselect_b32 s9, s53, s55
	s_cselect_b32 s12, s52, s54
	s_lshl_b64 s[10:11], s[10:11], 12
	s_add_u32 s10, s12, s10
	s_addc_u32 s11, s9, s11
	global_load_dwordx4 v[44:47], v64, s[10:11] nt
	global_load_dwordx4 v[40:43], v64, s[10:11] offset:1024 nt
	global_load_dwordx4 v[36:39], v64, s[10:11] offset:2048 nt
	global_load_dwordx4 v[32:35], v64, s[10:11] offset:3072 nt
	v_readlane_b32 s56, v249, 8
	v_readlane_b32 s57, v249, 9
	v_readlane_b32 s58, v249, 10
	v_readlane_b32 s59, v249, 11
	v_readlane_b32 s60, v249, 12
	v_readlane_b32 s61, v249, 13
	v_readlane_b32 s62, v249, 14
	v_readlane_b32 s63, v249, 15
	v_readlane_b32 s64, v249, 16
	v_readlane_b32 s65, v249, 17
	v_readlane_b32 s66, v249, 18
	v_readlane_b32 s67, v249, 19
.LBB0_71:
	s_add_i32 s12, s23, s0
	s_cmp_lt_i32 s12, 0x8080
	s_cselect_b64 s[16:17], -1, 0
	s_cmp_gt_i32 s12, 0x807f
	s_cbranch_scc1 .LBB0_73
	s_ashr_i32 s9, s12, 31
	s_add_i32 s10, s12, 0xffff8000
	s_cmp_lt_i32 s12, 0x8000
	v_readlane_b32 s52, v249, 4
	s_cselect_b32 s11, s9, 0
	s_cselect_b32 s10, s12, s10
	v_readlane_b32 s53, v249, 5
	v_readlane_b32 s54, v249, 6
	v_readlane_b32 s55, v249, 7
	s_cselect_b32 s9, s53, s55
	s_cselect_b32 s13, s52, s54
	s_lshl_b64 s[10:11], s[10:11], 12
	s_add_u32 s10, s13, s10
	s_addc_u32 s11, s9, s11
	global_load_dwordx4 v[28:31], v64, s[10:11] nt
	global_load_dwordx4 v[24:27], v64, s[10:11] offset:1024 nt
	global_load_dwordx4 v[20:23], v64, s[10:11] offset:2048 nt
	global_load_dwordx4 v[16:19], v64, s[10:11] offset:3072 nt
	v_readlane_b32 s56, v249, 8
	v_readlane_b32 s57, v249, 9
	v_readlane_b32 s58, v249, 10
	v_readlane_b32 s59, v249, 11
	v_readlane_b32 s60, v249, 12
	v_readlane_b32 s61, v249, 13
	v_readlane_b32 s62, v249, 14
	v_readlane_b32 s63, v249, 15
	v_readlane_b32 s64, v249, 16
	v_readlane_b32 s65, v249, 17
	v_readlane_b32 s66, v249, 18
	v_readlane_b32 s67, v249, 19
.LBB0_73:
	s_add_i32 s10, s24, s0
	s_cmp_lt_i32 s10, 0x8080
	s_cselect_b64 s[14:15], -1, 0
	s_cmp_gt_i32 s10, 0x807f
	s_cbranch_scc1 .LBB0_75
	s_ashr_i32 s9, s10, 31
	s_add_i32 s11, s10, 0xffff8000
	s_cmp_lt_i32 s10, 0x8000
	v_readlane_b32 s52, v249, 4
	s_cselect_b32 s21, s9, 0
	s_cselect_b32 s20, s10, s11
	v_readlane_b32 s53, v249, 5
	v_readlane_b32 s54, v249, 6
	v_readlane_b32 s55, v249, 7
	s_cselect_b32 s9, s53, s55
	s_cselect_b32 s11, s52, s54
	s_lshl_b64 s[20:21], s[20:21], 12
	s_add_u32 s20, s11, s20
	s_addc_u32 s21, s9, s21
	global_load_dwordx4 v[12:15], v64, s[20:21] nt
	global_load_dwordx4 v[8:11], v64, s[20:21] offset:1024 nt
	global_load_dwordx4 v[4:7], v64, s[20:21] offset:2048 nt
	global_load_dwordx4 v[0:3], v64, s[20:21] offset:3072 nt
	v_readlane_b32 s56, v249, 8
	v_readlane_b32 s57, v249, 9
	v_readlane_b32 s58, v249, 10
	v_readlane_b32 s59, v249, 11
	v_readlane_b32 s60, v249, 12
	v_readlane_b32 s61, v249, 13
	v_readlane_b32 s62, v249, 14
	v_readlane_b32 s63, v249, 15
	v_readlane_b32 s64, v249, 16
	v_readlane_b32 s65, v249, 17
	v_readlane_b32 s66, v249, 18
	v_readlane_b32 s67, v249, 19
